# P4b: raw V-row loads hoisted to the top of the tile loop (latency overlaps the c_kv rms chain)
# speedup vs baseline: 1.0128x; 1.0037x over previous
; __device__ __forceinline__ unsigned pk2(float a, float b) { f32x2_t v = {a, b}; bf16x2v_t r = __builtin_convertvector(v, bf16x2v_t); return __builtin_bit_cast(unsigned, r); }
; __device__ __forceinline__ float bf1(unsigned short u) { return __uint_as_float(((unsigned)u) << 16); }
; #define LAS __attribute__((address_space(3)))
; __device__ __forceinline__ void phase4b(const Args& a, LAS unsigned char* lds, int tid_) {
;     ...
;           for (int e = 0; e < 8; ++e) if (lane == e) rkl[wave * 8 + e] = rsqrtf(red[e] * (1.f / KVLORA) + EPS); }
; #pragma unroll
;         for (int i = 0; i < 8; ++i) { const int c = tid + 512 * i, tok = c >> 6, rem = c & 63, h = rem >> 4, part = rem & 15;
;             const u32x4 v = *(const u32x4*)(RAW + (size_t)(row0 + tok) * UPN + 768 + h * 256 + 128 + part * 8);
;             *(LAS u32x4*)(lds + tok * PITCH + (h * 128 + part * 8) * 2) = v; }
;         __syncthreads();
;         const int b = row0 / SEQ, s0 = row0 % SEQ, ch = tid & 7;
;         int key[8];
; #pragma unroll
;         for (int e = 0; e < 8; ++e) { const int p = ch * 8 + e, q = p & 15; key[e] = 16 * (p >> 4) + 8 * ((q & 7) >> 2) + 4 * (q >> 3) + (q & 3); }
;         float rk[8];
; #pragma unroll
;         for (int e = 0; e < 8; ++e) rk[e] = rkl[key[e]];
; #pragma unroll
;         for (int i = 0; i < 8; ++i) {
;             const int row = (tid >> 3) + 64 * i, h = row >> 7, d = row & 127;
;             unsigned w[4];
; #pragma unroll
;             for (int e = 0; e < 4; ++e) {
;                 const float lo = bf1(*(const LAS unsigned short*)(lds + key[2 * e] * PITCH + row * 2)) * rk[2 * e], hi = bf1(*(const LAS unsigned short*)(lds + key[2 * e + 1] * PITCH + row * 2)) * rk[2 * e + 1];
;                 w[e] = pk2(lo, hi);
;             }
;             *(u32x4*)(VT + ((size_t)(b * NH + h) * VD + d) * SEQ + s0 + ch * 8) = (u32x4){w[0], w[1], w[2], w[3]};
.LBB0_391:
	s_or_b64 exec, exec, s[0:1]
	v_add_u32_e32 v0, s8, v27
	v_mad_i64_i32 v[0:1], s[0:1], v0, s2, v[10:11]
	v_lshl_add_u64 v[0:1], v[0:1], 0, v[8:9]
	s_waitcnt lgkmcnt(4)
	v_add_co_u32_e32 v70, vcc, 0x9800000, v0
	v_add_u32_e32 v0, s8, v36
	s_nop 0
	v_addc_co_u32_e32 v71, vcc, 0, v1, vcc
	v_mad_i64_i32 v[0:1], s[0:1], v0, s2, v[10:11]
	v_lshl_add_u64 v[0:1], v[0:1], 0, v[8:9]
	v_add_co_u32_e32 v72, vcc, 0x9800000, v0
	s_waitcnt lgkmcnt(3)
	v_add_u32_e32 v23, s8, v37
	s_waitcnt lgkmcnt(2)
	v_addc_co_u32_e32 v73, vcc, 0, v1, vcc
	v_mad_i64_i32 v[70:71], s[0:1], v23, s2, v[10:11]
	v_lshl_add_u64 v[70:71], v[70:71], 0, v[8:9]
	v_add_co_u32_e32 v78, vcc, 0x9800000, v70
	v_add_u32_e32 v23, s8, v38
	s_nop 0
	v_addc_co_u32_e32 v79, vcc, 0, v71, vcc
	v_mad_i64_i32 v[70:71], s[0:1], v23, s2, v[10:11]
	v_lshl_add_u64 v[70:71], v[70:71], 0, v[8:9]
	v_add_co_u32_e32 v80, vcc, 0x9800000, v70
	v_add_u32_e32 v23, s8, v39
	s_nop 0
	v_addc_co_u32_e32 v81, vcc, 0, v71, vcc
	s_waitcnt lgkmcnt(0)
	v_mad_i64_i32 v[78:79], s[0:1], v23, s2, v[10:11]
	v_lshl_add_u64 v[78:79], v[78:79], 0, v[8:9]
	v_add_co_u32_e32 v86, vcc, 0x9800000, v78
	v_add_u32_e32 v23, s8, v40
	s_nop 0
	v_addc_co_u32_e32 v87, vcc, 0, v79, vcc
	v_mad_i64_i32 v[78:79], s[0:1], v23, s2, v[10:11]
	v_lshl_add_u64 v[78:79], v[78:79], 0, v[8:9]
	v_add_co_u32_e32 v88, vcc, 0x9800000, v78
	v_add_u32_e32 v23, s8, v41
	s_nop 0
	v_addc_co_u32_e32 v89, vcc, 0, v79, vcc
	v_mad_i64_i32 v[86:87], s[0:1], v23, s2, v[10:11]
	v_lshl_add_u64 v[86:87], v[86:87], 0, v[8:9]
	v_add_co_u32_e32 v94, vcc, 0x9800000, v86
	v_add_u32_e32 v23, s8, v42
	s_nop 0
	v_addc_co_u32_e32 v95, vcc, 0, v87, vcc
	v_mad_i64_i32 v[86:87], s[0:1], v23, s2, v[10:11]
	v_lshl_add_u64 v[86:87], v[86:87], 0, v[8:9]
	v_add_co_u32_e32 v96, vcc, 0x9800000, v86
	s_ashr_i32 s0, s14, 31
	s_nop 0
	v_addc_co_u32_e32 v97, vcc, 0, v87, vcc
	s_lshr_b32 s0, s0, 25
	s_add_i32 s0, s14, s0
	s_ashr_i32 s1, s0, 7
	s_ashr_i32 s0, s8, 31
	s_lshr_b32 s0, s0, 19
	s_add_i32 s0, s8, s0
	s_lshl_b32 s4, s1, 2
	s_and_b32 s0, s0, 0xffffe000
	s_sub_i32 s0, s8, s0
	s_ashr_i32 s1, s0, 31
	s_lshl_b64 s[0:1], s[0:1], 1
	s_add_i32 s14, s14, s88
	s_add_i32 s8, s8, s9
	s_cmpk_lt_i32 s14, 0x100
	s_waitcnt vmcnt(0)
	ds_write_b128 v54, v[130:133]
	s_waitcnt vmcnt(6)
	ds_write_b128 v55, v[134:137]
	s_waitcnt vmcnt(5)
	ds_write_b128 v56, v[138:141]
	s_waitcnt vmcnt(4)
	ds_write_b128 v57, v[142:145]
	s_waitcnt vmcnt(3)
	ds_write_b128 v58, v[146:149]
	s_waitcnt vmcnt(2)
	ds_write_b128 v59, v[150:153]
	s_waitcnt vmcnt(1)
	ds_write_b128 v60, v[154:157]
	s_waitcnt vmcnt(0)
	ds_write_b128 v61, v[158:161]
	s_waitcnt lgkmcnt(0)
	s_barrier
	ds_read_b128 v[0:3], v43
	ds_read_u16 v4, v62
	ds_read_u16 v5, v62 offset:1040
	ds_read_u16 v23, v62 offset:2080
	ds_read_u16 v25, v62 offset:3120
	ds_read_u16 v74, v62 offset:8320
	ds_read_u16 v75, v62 offset:9360
	ds_read_u16 v76, v62 offset:10400
	ds_read_u16 v77, v62 offset:11440
	s_waitcnt lgkmcnt(6)
	v_lshlrev_b32_e32 v71, 16, v5
	v_lshlrev_b32_e32 v70, 16, v4
	ds_read_b128 v[4:7], v44
	s_waitcnt lgkmcnt(5)
	v_lshlrev_b32_e32 v73, 16, v25
	v_lshlrev_b32_e32 v72, 16, v23
	v_pk_mul_f32 v[70:71], v[0:1], v[70:71]
	v_pk_mul_f32 v[72:73], v[2:3], v[72:73]
	v_cvt_pk_bf16_f32 v70, v70, v71
	v_cvt_pk_bf16_f32 v71, v72, v73
	s_waitcnt lgkmcnt(3)
	v_lshlrev_b32_e32 v73, 16, v75
	v_lshlrev_b32_e32 v72, 16, v74
	s_waitcnt lgkmcnt(1)
	v_lshlrev_b32_e32 v75, 16, v77
	v_lshlrev_b32_e32 v74, 16, v76
	s_waitcnt lgkmcnt(0)
	v_pk_mul_f32 v[72:73], v[4:5], v[72:73]
	v_pk_mul_f32 v[74:75], v[6:7], v[74:75]
	v_cvt_pk_bf16_f32 v72, v72, v73
	v_cvt_pk_bf16_f32 v73, v74, v75
	v_add_u32_e32 v74, s4, v45
	v_ashrrev_i32_e32 v75, 31, v74
	v_lshlrev_b64 v[74:75], 21, v[74:75]
	v_lshl_add_u64 v[74:75], v[12:13], 0, v[74:75]
	v_lshl_add_u64 v[74:75], v[74:75], 0, s[0:1]
	v_mov_b32_e32 v25, v9
	v_lshl_add_u64 v[74:75], v[74:75], 0, v[24:25]
	global_store_dwordx4 v[74:75], v[70:73], off
	ds_read_u16 v23, v63
	ds_read_u16 v70, v63 offset:1040
	ds_read_u16 v72, v63 offset:2080
	ds_read_u16 v73, v63 offset:3120
	ds_read_u16 v74, v63 offset:8320
	ds_read_u16 v75, v63 offset:9360
	ds_read_u16 v76, v63 offset:10400
	ds_read_u16 v77, v63 offset:11440
	s_waitcnt lgkmcnt(6)
	v_lshlrev_b32_e32 v71, 16, v70
	v_lshlrev_b32_e32 v70, 16, v23
	s_waitcnt lgkmcnt(4)
	v_lshlrev_b32_e32 v73, 16, v73
	v_lshlrev_b32_e32 v72, 16, v72
	v_pk_mul_f32 v[70:71], v[0:1], v[70:71]
	v_pk_mul_f32 v[72:73], v[2:3], v[72:73]
	v_cvt_pk_bf16_f32 v70, v70, v71
	v_cvt_pk_bf16_f32 v71, v72, v73
	s_waitcnt lgkmcnt(2)
	v_lshlrev_b32_e32 v73, 16, v75
	v_lshlrev_b32_e32 v72, 16, v74
	s_waitcnt lgkmcnt(0)
	v_lshlrev_b32_e32 v75, 16, v77
	v_lshlrev_b32_e32 v74, 16, v76
	v_pk_mul_f32 v[72:73], v[4:5], v[72:73]
	v_pk_mul_f32 v[74:75], v[6:7], v[74:75]
	v_cvt_pk_bf16_f32 v72, v72, v73
	v_cvt_pk_bf16_f32 v73, v74, v75
	v_add_u32_e32 v74, s4, v46
	v_ashrrev_i32_e32 v75, 31, v74
	v_lshlrev_b64 v[74:75], 21, v[74:75]
	v_lshl_add_u64 v[74:75], v[14:15], 0, v[74:75]
	v_lshl_add_u64 v[74:75], v[74:75], 0, s[0:1]
	v_lshl_add_u64 v[74:75], v[74:75], 0, v[24:25]
	global_store_dwordx4 v[74:75], v[70:73], off
	ds_read_u16 v23, v64
	ds_read_u16 v70, v64 offset:1040
	ds_read_u16 v72, v64 offset:2080
	ds_read_u16 v73, v64 offset:3120
	ds_read_u16 v74, v64 offset:8320
	ds_read_u16 v75, v64 offset:9360
	ds_read_u16 v76, v64 offset:10400
	ds_read_u16 v77, v64 offset:11440
	s_waitcnt lgkmcnt(6)
	v_lshlrev_b32_e32 v71, 16, v70
	v_lshlrev_b32_e32 v70, 16, v23
	s_waitcnt lgkmcnt(4)
	v_lshlrev_b32_e32 v73, 16, v73
	v_lshlrev_b32_e32 v72, 16, v72
	v_pk_mul_f32 v[70:71], v[0:1], v[70:71]
	v_pk_mul_f32 v[72:73], v[2:3], v[72:73]
	v_cvt_pk_bf16_f32 v70, v70, v71
	v_cvt_pk_bf16_f32 v71, v72, v73
	s_waitcnt lgkmcnt(2)
; __device__ __forceinline__ unsigned pk2(float a, float b) { f32x2_t v = {a, b}; bf16x2v_t r = __builtin_convertvector(v, bf16x2v_t); return __builtin_bit_cast(unsigned, r); }
; __device__ __forceinline__ float bf1(unsigned short u) { return __uint_as_float(((unsigned)u) << 16); }
; #define LAS __attribute__((address_space(3)))
; __device__ __forceinline__ void phase4b(const Args& a, LAS unsigned char* lds, int tid_) {
;     ...
;         for (int i = 0; i < 8; ++i) {
;             const int row = (tid >> 3) + 64 * i, h = row >> 7, d = row & 127;
;             unsigned w[4];
; #pragma unroll
;             for (int e = 0; e < 4; ++e) {
;                 const float lo = bf1(*(const LAS unsigned short*)(lds + key[2 * e] * PITCH + row * 2)) * rk[2 * e], hi = bf1(*(const LAS unsigned short*)(lds + key[2 * e + 1] * PITCH + row * 2)) * rk[2 * e + 1];
;                 w[e] = pk2(lo, hi);
;             }
;             *(u32x4*)(VT + ((size_t)(b * NH + h) * VD + d) * SEQ + s0 + ch * 8) = (u32x4){w[0], w[1], w[2], w[3]};
;         }
;         __syncthreads();
;     }
	v_lshlrev_b32_e32 v73, 16, v75
	v_lshlrev_b32_e32 v72, 16, v74
	s_waitcnt lgkmcnt(0)
	v_lshlrev_b32_e32 v75, 16, v77
	v_lshlrev_b32_e32 v74, 16, v76
	v_pk_mul_f32 v[72:73], v[4:5], v[72:73]
	v_pk_mul_f32 v[74:75], v[6:7], v[74:75]
	v_cvt_pk_bf16_f32 v72, v72, v73
	v_cvt_pk_bf16_f32 v73, v74, v75
	v_add_u32_e32 v74, s4, v47
	v_ashrrev_i32_e32 v75, 31, v74
	v_lshlrev_b64 v[74:75], 21, v[74:75]
	v_lshl_add_u64 v[74:75], v[12:13], 0, v[74:75]
	v_lshl_add_u64 v[74:75], v[74:75], 0, s[0:1]
	v_lshl_add_u64 v[74:75], v[74:75], 0, v[24:25]
	global_store_dwordx4 v[74:75], v[70:73], off
	ds_read_u16 v23, v65
	ds_read_u16 v70, v65 offset:1040
	ds_read_u16 v72, v65 offset:2080
	ds_read_u16 v73, v65 offset:3120
	ds_read_u16 v74, v65 offset:8320
	ds_read_u16 v75, v65 offset:9360
	ds_read_u16 v76, v65 offset:10400
	ds_read_u16 v77, v65 offset:11440
	s_waitcnt lgkmcnt(6)
	v_lshlrev_b32_e32 v71, 16, v70
	v_lshlrev_b32_e32 v70, 16, v23
	s_waitcnt lgkmcnt(4)
	v_lshlrev_b32_e32 v73, 16, v73
	v_lshlrev_b32_e32 v72, 16, v72
	v_pk_mul_f32 v[70:71], v[0:1], v[70:71]
	v_pk_mul_f32 v[72:73], v[2:3], v[72:73]
	v_cvt_pk_bf16_f32 v70, v70, v71
	v_cvt_pk_bf16_f32 v71, v72, v73
	s_waitcnt lgkmcnt(2)
	v_lshlrev_b32_e32 v73, 16, v75
	v_lshlrev_b32_e32 v72, 16, v74
	s_waitcnt lgkmcnt(0)
	v_lshlrev_b32_e32 v75, 16, v77
	v_lshlrev_b32_e32 v74, 16, v76
	v_pk_mul_f32 v[72:73], v[4:5], v[72:73]
	v_pk_mul_f32 v[74:75], v[6:7], v[74:75]
	v_cvt_pk_bf16_f32 v72, v72, v73
	v_cvt_pk_bf16_f32 v73, v74, v75
	v_add_u32_e32 v74, s4, v48
	v_ashrrev_i32_e32 v75, 31, v74
	v_lshlrev_b64 v[74:75], 21, v[74:75]
	v_lshl_add_u64 v[74:75], v[16:17], 0, v[74:75]
	v_lshl_add_u64 v[74:75], v[74:75], 0, s[0:1]
	v_lshl_add_u64 v[74:75], v[74:75], 0, v[24:25]
	global_store_dwordx4 v[74:75], v[70:73], off
	ds_read_u16 v23, v66
	ds_read_u16 v70, v66 offset:1040
	ds_read_u16 v72, v66 offset:2080
	ds_read_u16 v73, v66 offset:3120
	ds_read_u16 v74, v66 offset:8320
	ds_read_u16 v75, v66 offset:9360
	ds_read_u16 v76, v66 offset:10400
	ds_read_u16 v77, v66 offset:11440
	s_waitcnt lgkmcnt(6)
	v_lshlrev_b32_e32 v71, 16, v70
	v_lshlrev_b32_e32 v70, 16, v23
	s_waitcnt lgkmcnt(4)
	v_lshlrev_b32_e32 v73, 16, v73
	v_lshlrev_b32_e32 v72, 16, v72
	v_pk_mul_f32 v[70:71], v[0:1], v[70:71]
	v_pk_mul_f32 v[72:73], v[2:3], v[72:73]
	v_cvt_pk_bf16_f32 v70, v70, v71
	v_cvt_pk_bf16_f32 v71, v72, v73
	s_waitcnt lgkmcnt(2)
	v_lshlrev_b32_e32 v73, 16, v75
	v_lshlrev_b32_e32 v72, 16, v74
	s_waitcnt lgkmcnt(0)
	v_lshlrev_b32_e32 v75, 16, v77
	v_lshlrev_b32_e32 v74, 16, v76
	v_pk_mul_f32 v[72:73], v[4:5], v[72:73]
	v_pk_mul_f32 v[74:75], v[6:7], v[74:75]
	v_cvt_pk_bf16_f32 v72, v72, v73
	v_cvt_pk_bf16_f32 v73, v74, v75
	v_add_u32_e32 v74, s4, v49
	v_ashrrev_i32_e32 v75, 31, v74
	v_lshlrev_b64 v[74:75], 21, v[74:75]
	v_lshl_add_u64 v[74:75], v[12:13], 0, v[74:75]
	v_lshl_add_u64 v[74:75], v[74:75], 0, s[0:1]
	v_lshl_add_u64 v[74:75], v[74:75], 0, v[24:25]
	global_store_dwordx4 v[74:75], v[70:73], off
	ds_read_u16 v23, v67
	ds_read_u16 v70, v67 offset:1040
	ds_read_u16 v72, v67 offset:2080
	ds_read_u16 v73, v67 offset:3120
	ds_read_u16 v74, v67 offset:8320
	ds_read_u16 v75, v67 offset:9360
	ds_read_u16 v76, v67 offset:10400
	ds_read_u16 v77, v67 offset:11440
	s_waitcnt lgkmcnt(6)
	v_lshlrev_b32_e32 v71, 16, v70
	v_lshlrev_b32_e32 v70, 16, v23
	s_waitcnt lgkmcnt(4)
	v_lshlrev_b32_e32 v73, 16, v73
	v_lshlrev_b32_e32 v72, 16, v72
	v_pk_mul_f32 v[70:71], v[0:1], v[70:71]
	v_pk_mul_f32 v[72:73], v[2:3], v[72:73]
	v_cvt_pk_bf16_f32 v70, v70, v71
	v_cvt_pk_bf16_f32 v71, v72, v73
	s_waitcnt lgkmcnt(2)
	v_lshlrev_b32_e32 v73, 16, v75
	v_lshlrev_b32_e32 v72, 16, v74
	s_waitcnt lgkmcnt(0)
	v_lshlrev_b32_e32 v75, 16, v77
	v_lshlrev_b32_e32 v74, 16, v76
	v_pk_mul_f32 v[72:73], v[4:5], v[72:73]
	v_pk_mul_f32 v[74:75], v[6:7], v[74:75]
	v_cvt_pk_bf16_f32 v72, v72, v73
	v_cvt_pk_bf16_f32 v73, v74, v75
	v_add_u32_e32 v74, s4, v50
	v_ashrrev_i32_e32 v75, 31, v74
	v_lshlrev_b64 v[74:75], 21, v[74:75]
	v_lshl_add_u64 v[74:75], v[18:19], 0, v[74:75]
	v_lshl_add_u64 v[74:75], v[74:75], 0, s[0:1]
	v_lshl_add_u64 v[74:75], v[74:75], 0, v[24:25]
	global_store_dwordx4 v[74:75], v[70:73], off
	ds_read_u16 v23, v68
	ds_read_u16 v70, v68 offset:1040
	ds_read_u16 v72, v68 offset:2080
	ds_read_u16 v73, v68 offset:3120
	ds_read_u16 v74, v68 offset:8320
	ds_read_u16 v75, v68 offset:9360
	ds_read_u16 v76, v68 offset:10400
	ds_read_u16 v77, v68 offset:11440
	s_waitcnt lgkmcnt(6)
	v_lshlrev_b32_e32 v71, 16, v70
	v_lshlrev_b32_e32 v70, 16, v23
	s_waitcnt lgkmcnt(4)
	v_lshlrev_b32_e32 v73, 16, v73
	v_lshlrev_b32_e32 v72, 16, v72
	v_pk_mul_f32 v[70:71], v[0:1], v[70:71]
	v_pk_mul_f32 v[72:73], v[2:3], v[72:73]
	v_cvt_pk_bf16_f32 v70, v70, v71
	v_cvt_pk_bf16_f32 v71, v72, v73
	s_waitcnt lgkmcnt(2)
	v_lshlrev_b32_e32 v73, 16, v75
	v_lshlrev_b32_e32 v72, 16, v74
	s_waitcnt lgkmcnt(0)
	v_lshlrev_b32_e32 v75, 16, v77
	v_lshlrev_b32_e32 v74, 16, v76
	v_pk_mul_f32 v[72:73], v[4:5], v[72:73]
	v_pk_mul_f32 v[74:75], v[6:7], v[74:75]
	v_cvt_pk_bf16_f32 v72, v72, v73
	v_cvt_pk_bf16_f32 v73, v74, v75
	v_add_u32_e32 v74, s4, v51
	v_ashrrev_i32_e32 v75, 31, v74
	v_lshlrev_b64 v[74:75], 21, v[74:75]
	v_lshl_add_u64 v[74:75], v[12:13], 0, v[74:75]
	v_lshl_add_u64 v[74:75], v[74:75], 0, s[0:1]
	v_lshl_add_u64 v[74:75], v[74:75], 0, v[24:25]
	global_store_dwordx4 v[74:75], v[70:73], off
	ds_read_u16 v23, v69
	ds_read_u16 v70, v69 offset:1040
	ds_read_u16 v72, v69 offset:2080
	ds_read_u16 v73, v69 offset:3120
	ds_read_u16 v74, v69 offset:8320
	ds_read_u16 v75, v69 offset:9360
	ds_read_u16 v76, v69 offset:10400
	ds_read_u16 v77, v69 offset:11440
	s_waitcnt lgkmcnt(6)
	v_lshlrev_b32_e32 v71, 16, v70
	v_lshlrev_b32_e32 v70, 16, v23
	v_pk_mul_f32 v[0:1], v[0:1], v[70:71]
	s_waitcnt lgkmcnt(4)
	v_lshlrev_b32_e32 v71, 16, v73
	v_lshlrev_b32_e32 v70, 16, v72
	v_pk_mul_f32 v[2:3], v[2:3], v[70:71]
	v_cvt_pk_bf16_f32 v0, v0, v1
	v_cvt_pk_bf16_f32 v1, v2, v3
	s_waitcnt lgkmcnt(2)
	v_lshlrev_b32_e32 v3, 16, v75
	v_lshlrev_b32_e32 v2, 16, v74
	v_pk_mul_f32 v[2:3], v[4:5], v[2:3]
	s_waitcnt lgkmcnt(0)
	v_lshlrev_b32_e32 v5, 16, v77
	v_lshlrev_b32_e32 v4, 16, v76
	v_pk_mul_f32 v[4:5], v[6:7], v[4:5]
	v_cvt_pk_bf16_f32 v2, v2, v3
	v_cvt_pk_bf16_f32 v3, v4, v5
	v_add_u32_e32 v4, s4, v52
	v_ashrrev_i32_e32 v5, 31, v4
	v_lshlrev_b64 v[4:5], 21, v[4:5]
	v_lshl_add_u64 v[4:5], v[20:21], 0, v[4:5]
	v_lshl_add_u64 v[4:5], v[4:5], 0, s[0:1]
	v_lshl_add_u64 v[4:5], v[4:5], 0, v[24:25]
	global_store_dwordx4 v[4:5], v[0:3], off
	s_barrier
	s_cbranch_scc0 .LBB0_420
; __device__ __forceinline__ float bflo(unsigned u) { return __uint_as_float(u << 16); }
; __device__ __forceinline__ float bfhi(unsigned u) { return __uint_as_float(u & 0xffff0000u); }
; __device__ __forceinline__ void phase4b(const Args& a, LAS unsigned char* lds, int tid_) {
;     ...
;     for (int tile = blockIdx.x; tile < T / 64; tile += gridDim.x) {
;         const int row0 = tile * 64;
;         { float red[8];
; #pragma unroll
;           for (int e = 0; e < 8; ++e) { const unsigned c = *(const unsigned*)(PROJ + (size_t)(row0 + wave * 8 + e) * PP + C_CKV + 2 * lane); const float d0 = bflo(c), d1 = bfhi(c); red[e] = d0 * d0 + d1 * d1; }
; #pragma unroll
;           for (int o = 1; o < 64; o <<= 1) {
; #pragma unroll
;               for (int e = 0; e < 8; ++e) red[e] += __shfl_xor(red[e], o);
;           }
; #pragma unroll
;           for (int e = 0; e < 8; ++e) if (lane == e) rkl[wave * 8 + e] = rsqrtf(red[e] * (1.f / KVLORA) + EPS); }
; #pragma unroll
;         for (int i = 0; i < 8; ++i) { const int c = tid + 512 * i, tok = c >> 6, rem = c & 63, h = rem >> 4, part = rem & 15;
;             const u32x4 v = *(const u32x4*)(RAW + (size_t)(row0 + tok) * UPN + 768 + h * 256 + 128 + part * 8);
.LBB0_392:
	v_add_u32_e32 v120, s8, v27
	v_mad_i64_i32 v[120:121], s[100:101], v120, s2, v[10:11]
	v_lshl_add_u64 v[120:121], v[120:121], 0, v[8:9]
	v_add_co_u32_e32 v122, vcc, 0x9800000, v120
	s_nop 1
	v_addc_co_u32_e32 v123, vcc, 0, v121, vcc
	global_load_dwordx4 v[130:133], v[122:123], off offset:1792 nt
	v_add_u32_e32 v120, s8, v36
	v_mad_i64_i32 v[120:121], s[100:101], v120, s2, v[10:11]
	v_lshl_add_u64 v[120:121], v[120:121], 0, v[8:9]
	v_add_co_u32_e32 v122, vcc, 0x9800000, v120
	s_nop 1
	v_addc_co_u32_e32 v123, vcc, 0, v121, vcc
	global_load_dwordx4 v[134:137], v[122:123], off offset:1792 nt
	v_add_u32_e32 v120, s8, v37
	v_mad_i64_i32 v[120:121], s[100:101], v120, s2, v[10:11]
	v_lshl_add_u64 v[120:121], v[120:121], 0, v[8:9]
	v_add_co_u32_e32 v122, vcc, 0x9800000, v120
	s_nop 1
	v_addc_co_u32_e32 v123, vcc, 0, v121, vcc
	global_load_dwordx4 v[138:141], v[122:123], off offset:1792 nt
	v_add_u32_e32 v120, s8, v38
	v_mad_i64_i32 v[120:121], s[100:101], v120, s2, v[10:11]
	v_lshl_add_u64 v[120:121], v[120:121], 0, v[8:9]
	v_add_co_u32_e32 v122, vcc, 0x9800000, v120
	s_nop 1
	v_addc_co_u32_e32 v123, vcc, 0, v121, vcc
	global_load_dwordx4 v[142:145], v[122:123], off offset:1792 nt
	v_add_u32_e32 v120, s8, v39
	v_mad_i64_i32 v[120:121], s[100:101], v120, s2, v[10:11]
	v_lshl_add_u64 v[120:121], v[120:121], 0, v[8:9]
	v_add_co_u32_e32 v122, vcc, 0x9800000, v120
	s_nop 1
	v_addc_co_u32_e32 v123, vcc, 0, v121, vcc
	global_load_dwordx4 v[146:149], v[122:123], off offset:1792 nt
	v_add_u32_e32 v120, s8, v40
	v_mad_i64_i32 v[120:121], s[100:101], v120, s2, v[10:11]
	v_lshl_add_u64 v[120:121], v[120:121], 0, v[8:9]
	v_add_co_u32_e32 v122, vcc, 0x9800000, v120
	s_nop 1
	v_addc_co_u32_e32 v123, vcc, 0, v121, vcc
	global_load_dwordx4 v[150:153], v[122:123], off offset:1792 nt
	v_add_u32_e32 v120, s8, v41
	v_mad_i64_i32 v[120:121], s[100:101], v120, s2, v[10:11]
	v_lshl_add_u64 v[120:121], v[120:121], 0, v[8:9]
	v_add_co_u32_e32 v122, vcc, 0x9800000, v120
	s_nop 1
	v_addc_co_u32_e32 v123, vcc, 0, v121, vcc
	global_load_dwordx4 v[154:157], v[122:123], off offset:1792 nt
	v_add_u32_e32 v120, s8, v42
	v_mad_i64_i32 v[120:121], s[100:101], v120, s2, v[10:11]
	v_lshl_add_u64 v[120:121], v[120:121], 0, v[8:9]
	v_add_co_u32_e32 v122, vcc, 0x9800000, v120
	s_nop 1
	v_addc_co_u32_e32 v123, vcc, 0, v121, vcc
	global_load_dwordx4 v[158:161], v[122:123], off offset:1792 nt
	v_add_u32_e32 v0, s8, v28
	v_ashrrev_i32_e32 v1, 31, v0
	v_lshlrev_b64 v[2:3], 12, v[0:1]
	v_add_u32_e32 v4, 1, v0
	v_lshl_add_u64 v[2:3], s[82:83], 0, v[2:3]
	v_mov_b32_e32 v23, v9
	v_ashrrev_i32_e32 v5, 31, v4
	v_lshl_add_u64 v[2:3], v[2:3], 0, v[22:23]
	v_lshlrev_b64 v[4:5], 12, v[4:5]
	v_add_u32_e32 v6, 2, v0
	v_add_co_u32_e32 v2, vcc, 0x3800000, v2
	v_lshl_add_u64 v[4:5], s[82:83], 0, v[4:5]
	v_ashrrev_i32_e32 v7, 31, v6
	v_addc_co_u32_e32 v3, vcc, 0, v3, vcc
	v_lshl_add_u64 v[4:5], v[4:5], 0, v[22:23]
	v_lshlrev_b64 v[6:7], 12, v[6:7]
	v_add_u32_e32 v70, 3, v0
	v_add_co_u32_e32 v4, vcc, s10, v4
	v_lshl_add_u64 v[6:7], s[82:83], 0, v[6:7]
	v_ashrrev_i32_e32 v71, 31, v70
	v_addc_co_u32_e32 v5, vcc, 0, v5, vcc
	v_lshl_add_u64 v[6:7], v[6:7], 0, v[22:23]
	v_lshlrev_b64 v[70:71], 12, v[70:71]
	v_add_co_u32_e32 v6, vcc, s10, v6
	v_lshl_add_u64 v[70:71], s[82:83], 0, v[70:71]
	s_nop 0
	v_addc_co_u32_e32 v7, vcc, 0, v7, vcc
	v_lshl_add_u64 v[70:71], v[70:71], 0, v[22:23]
	v_add_co_u32_e32 v70, vcc, s10, v70
	s_nop 1
	v_addc_co_u32_e32 v71, vcc, 0, v71, vcc
	global_load_dword v25, v[2:3], off offset:512
	global_load_dword v72, v[4:5], off offset:512
	global_load_dword v73, v[6:7], off offset:512
	global_load_dword v74, v[70:71], off offset:512
	v_add_u32_e32 v2, 4, v0
	v_ashrrev_i32_e32 v3, 31, v2
	v_lshlrev_b64 v[2:3], 12, v[2:3]
	v_add_u32_e32 v4, 5, v0
	v_lshl_add_u64 v[2:3], s[82:83], 0, v[2:3]
	v_ashrrev_i32_e32 v5, 31, v4
	v_lshl_add_u64 v[2:3], v[2:3], 0, v[22:23]
	v_lshlrev_b64 v[4:5], 12, v[4:5]
	v_add_u32_e32 v6, 6, v0
	v_add_co_u32_e32 v2, vcc, s10, v2
	v_lshl_add_u64 v[4:5], s[82:83], 0, v[4:5]
	v_ashrrev_i32_e32 v7, 31, v6
	v_addc_co_u32_e32 v3, vcc, 0, v3, vcc
	v_lshl_add_u64 v[4:5], v[4:5], 0, v[22:23]
	v_lshlrev_b64 v[6:7], 12, v[6:7]
	v_add_u32_e32 v0, 7, v0
	v_add_co_u32_e32 v4, vcc, s10, v4
	v_lshl_add_u64 v[6:7], s[82:83], 0, v[6:7]
	v_ashrrev_i32_e32 v1, 31, v0
	v_addc_co_u32_e32 v5, vcc, 0, v5, vcc
	v_lshl_add_u64 v[6:7], v[6:7], 0, v[22:23]
	v_lshlrev_b64 v[0:1], 12, v[0:1]
	v_add_co_u32_e32 v6, vcc, s10, v6
	v_lshl_add_u64 v[0:1], s[82:83], 0, v[0:1]
	s_nop 0
	v_addc_co_u32_e32 v7, vcc, 0, v7, vcc
	v_lshl_add_u64 v[0:1], v[0:1], 0, v[22:23]
	global_load_dword v70, v[2:3], off offset:512
	global_load_dword v71, v[4:5], off offset:512
	global_load_dword v75, v[6:7], off offset:512
	v_add_co_u32_e32 v0, vcc, s10, v0
	s_waitcnt vmcnt(6)
	v_and_b32_e32 v2, 0xffff0000, v25
	v_addc_co_u32_e32 v1, vcc, 0, v1, vcc
	global_load_dword v0, v[0:1], off offset:512
	v_lshlrev_b32_e32 v1, 16, v25
	v_mul_f32_e32 v2, v2, v2
	s_waitcnt vmcnt(6)
; __device__ __forceinline__ float bflo(unsigned u) { return __uint_as_float(u << 16); }
; __device__ __forceinline__ float bfhi(unsigned u) { return __uint_as_float(u & 0xffff0000u); }
; __device__ __forceinline__ void phase4b(const Args& a, LAS unsigned char* lds, int tid_) {
;     ...
;           for (int e = 0; e < 8; ++e) { const unsigned c = *(const unsigned*)(PROJ + (size_t)(row0 + wave * 8 + e) * PP + C_CKV + 2 * lane); const float d0 = bflo(c), d1 = bfhi(c); red[e] = d0 * d0 + d1 * d1; }
; #pragma unroll
;           for (int o = 1; o < 64; o <<= 1) {
; #pragma unroll
;               for (int e = 0; e < 8; ++e) red[e] += __shfl_xor(red[e], o);
;           }
; #pragma unroll
;           for (int e = 0; e < 8; ++e) if (lane == e) rkl[wave * 8 + e] = rsqrtf(red[e] * (1.f / KVLORA) + EPS); }
	v_and_b32_e32 v3, 0xffff0000, v72
	v_fmac_f32_e32 v2, v1, v1
	v_lshlrev_b32_e32 v1, 16, v72
	v_mul_f32_e32 v3, v3, v3
	s_waitcnt vmcnt(5)
	v_and_b32_e32 v4, 0xffff0000, v73
	v_fmac_f32_e32 v3, v1, v1
	v_lshlrev_b32_e32 v1, 16, v73
	v_mul_f32_e32 v4, v4, v4
	s_waitcnt vmcnt(4)
	v_and_b32_e32 v5, 0xffff0000, v74
	v_fmac_f32_e32 v4, v1, v1
	v_lshlrev_b32_e32 v1, 16, v74
	v_mul_f32_e32 v5, v5, v5
	v_fmac_f32_e32 v5, v1, v1
	ds_bpermute_b32 v25, v30, v3
	v_cmp_lt_i32_e32 vcc, 3, v26
	s_waitcnt vmcnt(3)
	v_and_b32_e32 v6, 0xffff0000, v70
	v_lshlrev_b32_e32 v1, 16, v70
	v_mul_f32_e32 v6, v6, v6
	s_waitcnt vmcnt(2)
	v_and_b32_e32 v7, 0xffff0000, v71
	v_fmac_f32_e32 v6, v1, v1
	v_lshlrev_b32_e32 v1, 16, v71
	v_mul_f32_e32 v7, v7, v7
	s_waitcnt vmcnt(1)
	v_and_b32_e32 v23, 0xffff0000, v75
	v_fmac_f32_e32 v7, v1, v1
	v_lshlrev_b32_e32 v1, 16, v75
	v_mul_f32_e32 v23, v23, v23
	v_fmac_f32_e32 v23, v1, v1
	ds_bpermute_b32 v70, v30, v4
	ds_bpermute_b32 v71, v30, v5
	ds_bpermute_b32 v72, v30, v6
	s_waitcnt vmcnt(0)
	v_lshlrev_b32_e32 v1, 16, v0
	v_and_b32_e32 v0, 0xffff0000, v0
	v_mul_f32_e32 v0, v0, v0
	v_fmac_f32_e32 v0, v1, v1
	ds_bpermute_b32 v1, v30, v2
	s_waitcnt lgkmcnt(0)
	v_add_f32_e32 v1, v2, v1
	v_add_f32_e32 v2, v3, v25
	v_add_f32_e32 v3, v4, v70
	v_add_f32_e32 v4, v5, v71
	v_add_f32_e32 v5, v6, v72
	ds_bpermute_b32 v6, v30, v7
	ds_bpermute_b32 v25, v30, v23
	ds_bpermute_b32 v70, v30, v0
	ds_bpermute_b32 v71, v31, v1
	ds_bpermute_b32 v72, v31, v2
	s_waitcnt lgkmcnt(4)
	v_add_f32_e32 v6, v7, v6
	s_waitcnt lgkmcnt(3)
	v_add_f32_e32 v7, v23, v25
	ds_bpermute_b32 v23, v31, v3
	ds_bpermute_b32 v25, v31, v4
	s_waitcnt lgkmcnt(4)
	v_add_f32_e32 v0, v0, v70
	s_waitcnt lgkmcnt(3)
	v_add_f32_e32 v1, v1, v71
	s_waitcnt lgkmcnt(2)
	v_add_f32_e32 v2, v2, v72
	ds_bpermute_b32 v70, v31, v5
	ds_bpermute_b32 v71, v31, v6
	ds_bpermute_b32 v72, v31, v7
	s_waitcnt lgkmcnt(4)
	v_add_f32_e32 v3, v3, v23
	s_waitcnt lgkmcnt(3)
	v_add_f32_e32 v4, v4, v25
	ds_bpermute_b32 v23, v31, v0
	ds_bpermute_b32 v25, v32, v1
	s_waitcnt lgkmcnt(4)
	v_add_f32_e32 v5, v5, v70
	s_waitcnt lgkmcnt(3)
	v_add_f32_e32 v6, v6, v71
	s_waitcnt lgkmcnt(2)
	v_add_f32_e32 v7, v7, v72
	ds_bpermute_b32 v70, v32, v2
	ds_bpermute_b32 v71, v32, v3
	ds_bpermute_b32 v72, v32, v4
	s_waitcnt lgkmcnt(4)
	v_add_f32_e32 v0, v0, v23
	s_waitcnt lgkmcnt(3)
	v_add_f32_e32 v1, v1, v25
	ds_bpermute_b32 v23, v32, v5
	ds_bpermute_b32 v25, v32, v6
	s_waitcnt lgkmcnt(4)
	v_add_f32_e32 v2, v2, v70
	s_waitcnt lgkmcnt(3)
	v_add_f32_e32 v3, v3, v71
	s_waitcnt lgkmcnt(2)
	v_add_f32_e32 v4, v4, v72
	ds_bpermute_b32 v70, v32, v7
	ds_bpermute_b32 v71, v32, v0
	ds_bpermute_b32 v72, v33, v1
	s_waitcnt lgkmcnt(4)
	v_add_f32_e32 v5, v5, v23
	s_waitcnt lgkmcnt(3)
	v_add_f32_e32 v6, v6, v25
	ds_bpermute_b32 v23, v33, v2
	ds_bpermute_b32 v25, v33, v3
	s_waitcnt lgkmcnt(4)
	v_add_f32_e32 v7, v7, v70
	s_waitcnt lgkmcnt(3)
	v_add_f32_e32 v0, v0, v71
	s_waitcnt lgkmcnt(2)
	v_add_f32_e32 v1, v1, v72
	ds_bpermute_b32 v70, v33, v4
	ds_bpermute_b32 v71, v33, v5
	ds_bpermute_b32 v72, v33, v6
	s_waitcnt lgkmcnt(4)
	v_add_f32_e32 v2, v2, v23
	s_waitcnt lgkmcnt(3)
	v_add_f32_e32 v3, v3, v25
	ds_bpermute_b32 v23, v33, v7
	ds_bpermute_b32 v25, v33, v0
	s_waitcnt lgkmcnt(4)
	v_add_f32_e32 v4, v4, v70
	s_waitcnt lgkmcnt(3)
	v_add_f32_e32 v5, v5, v71
	s_waitcnt lgkmcnt(2)
	v_add_f32_e32 v6, v6, v72
	ds_bpermute_b32 v70, v34, v1
	ds_bpermute_b32 v71, v34, v2
	ds_bpermute_b32 v72, v34, v3
	s_waitcnt lgkmcnt(4)
	v_add_f32_e32 v23, v7, v23
	s_waitcnt lgkmcnt(3)
	v_add_f32_e32 v73, v0, v25
	s_waitcnt lgkmcnt(2)
	v_add_f32_e32 v0, v1, v70
	s_waitcnt lgkmcnt(1)
	v_add_f32_e32 v1, v2, v71
	s_waitcnt lgkmcnt(0)
	v_add_f32_e32 v2, v3, v72
	ds_bpermute_b32 v3, v34, v4
	ds_bpermute_b32 v25, v34, v5
	ds_bpermute_b32 v70, v34, v6
	ds_bpermute_b32 v71, v34, v23
	ds_bpermute_b32 v72, v34, v73
	s_waitcnt lgkmcnt(4)
	v_add_f32_e32 v7, v4, v3
	s_waitcnt lgkmcnt(3)
	v_add_f32_e32 v4, v5, v25
	s_waitcnt lgkmcnt(2)
	v_add_f32_e32 v25, v6, v70
	s_waitcnt lgkmcnt(1)
	v_add_f32_e32 v71, v23, v71
	s_waitcnt lgkmcnt(0)
	v_add_f32_e32 v72, v73, v72
	ds_bpermute_b32 v3, v35, v0
	ds_bpermute_b32 v5, v35, v1
	ds_bpermute_b32 v6, v35, v2
	ds_bpermute_b32 v70, v35, v7
	ds_bpermute_b32 v23, v35, v4
	ds_bpermute_b32 v73, v35, v25
	ds_bpermute_b32 v74, v35, v71
	ds_bpermute_b32 v75, v35, v72
	s_and_saveexec_b64 s[0:1], vcc
	s_xor_b64 s[0:1], exec, s[0:1]
	s_cbranch_execz .LBB0_408
	v_cmp_lt_i32_e32 vcc, 5, v26
	s_and_saveexec_b64 s[4:5], vcc
	s_xor_b64 s[4:5], exec, s[4:5]
	s_cbranch_execz .LBB0_401
	v_cmp_lt_i32_e32 vcc, 6, v26
	s_and_saveexec_b64 s[6:7], vcc
	s_xor_b64 s[6:7], exec, s[6:7]
	s_cbranch_execz .LBB0_398
	v_cmp_eq_u32_e32 vcc, 7, v26
	s_and_saveexec_b64 s[12:13], vcc
	s_cbranch_execz .LBB0_397
	s_waitcnt lgkmcnt(0)
	v_add_f32_e32 v0, v72, v75
	v_fmamk_f32 v0, v0, 0x3c000000, v53
	v_mul_f32_e32 v1, 0x4b800000, v0
	v_cmp_gt_f32_e32 vcc, s11, v0
	s_nop 1
	v_cndmask_b32_e32 v0, v0, v1, vcc
	v_rsq_f32_e32 v0, v0
	s_nop 0
	v_mul_f32_e32 v1, 0x45800000, v0
	v_cndmask_b32_e32 v0, v0, v1, vcc
	v_add_u32_e32 v1, s3, v29
	ds_write_b32 v1, v0 offset:28
